# MLA K tile LDS swizzle made conflict-free (chunk xor row&15) on top of previous best
# baseline (speedup 1.0000x reference)
; template <int TYPE>
; __device__ __forceinline__ void attn_item(const Params& p, int layer, int head, int qb, int mode, LAS unsigned char* lds) {
;     constexpr int DQK = TYPE == 0 ? 192 : 128, NQ = DQK / 16, SHM_K = 64 * DQK * 2;
;     constexpr int OFF_K = 2 * SHM_V, OFF_B = OFF_K + 2 * SHM_K;
;     const int tid = opaque_tid(), wid = __builtin_amdgcn_readfirstlane(tid >> 6), lane = tid & 63, r32 = lane & 31, hi = lane >> 5;
;     const int P0 = qb * 256, qrow = P0 + wid * 32 + r32;
;     const bf16_t* Qb; int ldq; const bf16_t* Kn; int ldk; const bf16_t* Vp; int ldv;
;     if (TYPE == 0) { Qb = (const bf16_t*)(p.ws + WS_QM) + head * 192; ldq = 1536; Kn = (const bf16_t*)(p.ws + WS_KV) + head * 256; ldk = 2048; Vp = Kn + 128; ldv = 2048; }
;     else { Qb = (const bf16_t*)(p.ws + WS_QF) + head * 128; ldq = 1024; Kn = (const bf16_t*)(p.ws + WS_KF) + head * 128; ldk = 1024; Vp = (const bf16_t*)(p.ws + WS_Z) + 3072 + head * 128; ldv = ZLD; }
;     const bf16_t* Krp = (const bf16_t*)(p.ws + WS_KR);
;     const float* bias = (const float*)(p.ws + WS_BK) + (size_t)head * MROWS;
;     ...
;     const int my_kmax = KMAX(qrow);
;     const int w_first = KMAX(P0 + wid * 32), w_last = KMAX(P0 + wid * 32 + 31);
;     int blk_kmax = KMAX(P0 + 255); if (blk_kmax > MROWS - 1) blk_kmax = MROWS - 1;
;     const int NT = blk_kmax / 64 + 1;
;     bf16x8 qr[NQ];
; #pragma unroll
;     for (int d0 = 0; d0 < NQ; ++d0) qr[d0] = *(const bf16x8*)(Qb + (size_t)qrow * ldq + d0 * 16 + hi * 8);
;     LAS unsigned char* V_lds = lds; LAS unsigned char* K_lds = lds + OFF_K; LAS float* B_lds = (LAS float*)(lds + OFF_B);
;     LAS float* wsl = (LAS float*)(lds + LDS_BYTES - 4096) + wid * 64;
;     const int vb0 = (int)(unsigned)(uintptr_t)V_lds + v_rd_base(lane);
;     unsigned offK[2], offV[2], offR;
; #pragma unroll
;     for (int j = 0; j < 2; ++j) {
;         const int row = (j * 8 + wid) * 4 + (lane >> 4), ch = (lane & 15) ^ (row & 7);
;         offK[j] = (unsigned)(row * ldk + ch * 8) * 2u;
;         const int q = (j * 8 + wid) * 64 + lane, sub = q >> 5, kk = (sub >> 2) * 8 + ((q & 31) >> 2), c = (sub & 3) * 32 + (q & 3) * 8;
;         const int k = (kk & ~0xC) | ((kk & 4) << 1) | ((kk & 8) >> 1);
;         offV[j] = (unsigned)(k * ldv + c) * 2u;
;     }
;     { const int row = wid * 8 + (lane >> 3), ch = (lane & 7) ^ (row & 7); offR = (unsigned)(row * 64 + ch * 8) * 2u; }
.LBB0_813:
	s_or_b64 exec, exec, s[0:1]
	v_readlane_b32 s0, v254, 10
	s_waitcnt vmcnt(0) lgkmcnt(0)
	s_barrier
	v_mov_b32_e32 v0, s0
	ds_read_b32 v0, v0
	s_movk_i32 s0, 0x2d7
	s_waitcnt lgkmcnt(0)
	s_barrier
	v_cmp_lt_i32_e32 vcc, s0, v0
	v_readfirstlane_b32 s42, v0
	s_mov_b64 s[0:1], -1
	s_cbranch_vccnz .LBB0_810
	s_cmpk_gt_i32 s42, 0x107
	s_cbranch_scc0 .LBB0_842
	s_add_i32 s0, s42, 0xfffffef8
	s_lshr_b32 s2, s0, 3
	s_getpc_b64 s[0:1]
	s_add_u32 s0, s0, MLA_ORDER@rel32@lo+4
	s_addc_u32 s1, s1, MLA_ORDER@rel32@hi+12
	v_mov_b32_e32 v0, s2
	global_load_sbyte v9, v0, s[0:1]
	v_mov_b32_e32 v2, v210
	s_and_b32 s5, s42, 7
	v_readfirstlane_b32 s6, v2
	s_ashr_i32 s13, s6, 6
	s_lshl_b32 s4, s13, 5
	s_mul_i32 s3, s5, 0x180
	v_and_b32_e32 v226, 31, v2
	v_and_b32_e32 v227, 63, v2
	v_lshlrev_b32_e32 v5, 3, v2
	v_bfe_u32 v225, v2, 5, 1
	v_bfe_u32 v223, v2, 4, 2
	v_and_b32_e32 v5, 24, v5
	s_movk_i32 s30, 0x60
	v_lshrrev_b32_e32 v6, 1, v2
	v_lshlrev_b32_e32 v0, 4, v225
	v_and_b32_e32 v224, 15, v2
	v_bfe_u32 v3, v2, 2, 2
	v_and_b32_e32 v4, 32, v2
	v_and_b32_e32 v6, 8, v6
	v_or_b32_e32 v13, v6, v3
	s_mov_b64 s[36:37], 0x100
	v_bfe_u32 v7, v2, 3, 3
	v_bitop3_b32 v8, v7, v2, 7 bitop3:0x78
	v_lshlrev_b32_e32 v7, 7, v7
	v_lshlrev_b32_e32 v8, 4, v8
	s_waitcnt vmcnt(0)
	v_readfirstlane_b32 s1, v9
	s_and_b32 s25, s1, 63
	s_lshl_b32 s2, s25, 8
	s_and_b32 s0, s1, 0xff
	s_bfe_u32 s24, s1, 0x20006
	s_add_i32 s2, s4, s2
	s_add_u32 s10, s21, s3
	v_readlane_b32 s3, v254, 60
	s_addc_u32 s11, s3, 0
	v_or_b32_e32 v9, s2, v226
	s_lshl_b32 s19, s5, 9
	v_readlane_b32 s3, v254, 61
	v_mov_b64_e32 v[10:11], s[10:11]
	s_movk_i32 s11, 0xc00
	s_add_u32 s7, s3, s19
	v_readlane_b32 s3, v254, 62
	v_mad_i64_i32 v[10:11], s[28:29], v9, s11, v[10:11]
	s_addc_u32 s10, s3, 0
	s_lshl_b32 s3, s25, 2
	s_and_b32 s28, s6, 0x3fffffc0
	s_lshl_b32 s14, s13, 1
	s_add_i32 s29, s13, 8
	s_lshl_b32 s12, s13, 2
	s_and_b32 s11, s6, 64
	s_add_i32 s6, s3, 4
	s_and_b32 s18, s14, 4
	s_lshl_b32 s3, s29, 2
	v_lshl_or_b32 v14, s29, 6, v227
	s_lshl_b32 s14, s29, 1
	s_lshl_b32 s28, s28, 2
	v_or_b32_e32 v12, s12, v223
	s_and_b32 s12, s12, 0xffff0
	v_or_b32_e32 v15, s3, v223
	v_and_or_b32 v14, v14, s30, v5
	s_and_b32 s30, s3, 0xffff0
	s_and_b32 s31, s14, 4
	s_add_i32 s3, s28, 0
	v_lshl_add_u64 v[10:11], v[10:11], 0, v[0:1]
	s_or_b32 s29, s12, s18
	s_or_b32 s14, s30, s31
	s_add_i32 s3, s3, 0x1f000
	v_or3_b32 v9, v4, s11, v5
	global_load_dwordx4 v[130:133], v[10:11], off
	global_load_dwordx4 v[134:137], v[10:11], off offset:32
	global_load_dwordx4 v[138:141], v[10:11], off offset:64
	global_load_dwordx4 v[142:145], v[10:11], off offset:96
	global_load_dwordx4 v[146:149], v[10:11], off offset:128
	global_load_dwordx4 v[150:153], v[10:11], off offset:160
	global_load_dwordx4 v[154:157], v[10:11], off offset:192
	global_load_dwordx4 v[158:161], v[10:11], off offset:224
	global_load_dwordx4 v[162:165], v[10:11], off offset:256
	global_load_dwordx4 v[166:169], v[10:11], off offset:288
	global_load_dwordx4 v[170:173], v[10:11], off offset:320
	global_load_dwordx4 v[174:177], v[10:11], off offset:352
	v_bitop3_b32 v10, v12, v224, 15 bitop3:0x6c
	s_cmp_lt_u32 s25, 33
	v_lshlrev_b32_e32 v11, 1, v9
	v_lshlrev_b32_e32 v9, 4, v10
	v_or_b32_e32 v10, s29, v13
	s_cselect_b32 s33, s6, 0x84
	v_lshl_or_b32 v17, v12, 12, v9
	v_lshl_or_b32 v12, v10, 12, v11
	v_or_b32_e32 v11, s14, v13
	s_add_i32 s14, s33, 4
	s_lshl_b32 s6, s13, 10
	s_lshr_b32 s14, s14, 1
	s_cmp_eq_u32 s24, 1
	s_sext_i32_i16 s1, s1
	s_cselect_b32 s40, s14, s33
	s_cmp_lt_i32 s1, 0
	s_cselect_b32 s14, s14, 3
	s_lshl_b64 s[38:39], s[14:15], 18
	s_add_u32 s28, s7, s38
	s_addc_u32 s29, s10, s39
	s_and_b32 s1, s14, 1
	s_mul_i32 s7, s1, 0x6000
	s_add_i32 s7, s7, 0
	s_lshl_b32 s1, s1, 13
	s_add_i32 s7, s7, s6
	v_mov_b32_e32 v13, v1
	v_bitop3_b32 v16, v15, v224, 15 bitop3:0x6c
	s_add_i32 m0, s7, 0x8000
	v_lshl_add_u64 v[12:13], s[28:29], 0, v[12:13]
	s_sub_i32 s1, s7, s1
	v_lshlrev_b32_e32 v10, 4, v16
	global_load_lds_dwordx4 v17, s[28:29]
	v_lshl_add_u64 v[12:13], v[12:13], 0, s[36:37]
	s_mov_b32 m0, s1
	v_lshlrev_b32_e32 v14, 1, v14
	v_lshl_or_b32 v15, v15, 12, v10
	global_load_lds_dwordx4 v[12:13], off
	s_add_i32 m0, s7, 0xa000
	v_lshl_or_b32 v14, v11, 12, v14
	global_load_lds_dwordx4 v15, s[28:29]
	v_mov_b32_e32 v15, v1
	s_add_i32 m0, s1, 0x2000
	v_lshl_add_u64 v[12:13], s[28:29], 0, v[14:15]
	s_cmp_gt_u32 s0, 63
	v_lshl_add_u64 v[12:13], v[12:13], 0, s[36:37]
	s_cselect_b64 s[36:37], -1, 0
	s_cmp_lt_u32 s0, 64
	s_cselect_b32 s7, s33, s40
	s_lshl_b64 s[40:41], s[14:15], 13
	v_readlane_b32 s0, v254, 63
	s_add_u32 s0, s0, s40
	v_readlane_b32 s1, v255, 0
	s_addc_u32 s1, s1, s41
	s_bitcmp1_b32 s14, 0
	s_cselect_b32 s10, 0x6000, 0
	s_add_i32 s10, s10, 0
	s_add_i32 s10, s10, s6
	v_or3_b32 v11, v8, v7, s6
	global_load_lds_dwordx4 v[12:13], off
	s_add_i32 m0, s10, 0xc000
	s_sub_i32 s7, s7, s14
	global_load_lds_dwordx4 v11, s[0:1]
	s_waitcnt vmcnt(0)
	s_cmp_lt_i32 s7, 1
	v_cmp_gt_u32_e64 s[0:1], 32, v227
	s_waitcnt vmcnt(0) lgkmcnt(0)
	s_barrier
; #define LAS __attribute__((address_space(3)))
; template <int TYPE>
; __device__ __forceinline__ void attn_item(const Params& p, int layer, int head, int qb, int mode, LAS unsigned char* lds) {
;     ...
;     float m_reg = -1e30f, l_reg = 0.f; f32x16 o[4];
; #pragma unroll
;     for (int d = 0; d < 4; ++d) o[d] = (f32x16){};
;     constexpr int T0 = PADR / 64;
;     int tbeg = T0; float Bb = 0.f;
;     if (TYPE == 1) {
;         const float* gq = p.in[I_GFQ] + layer * 128; const float* gk = p.in[I_GFK] + layer * 128;
;         float gm = fmaxf(fabsf(gq[lane] * gk[lane]), fabsf(gq[lane + 64] * gk[lane + 64]));
; #pragma unroll
;         for (int o_ = 32; o_ >= 1; o_ >>= 1) gm = fmaxf(gm, __shfl_xor(gm, o_));
;         Bb = gm * 11.313708498984761f * LOG2E * 1.02f;
;     }
;     int tend = NT;
;     if (TYPE == 0 && mode != 0) { const int mid = (T0 + NT + 1) >> 1; if (mode == 1) tend = mid; else tbeg = mid; }
;     const int ntiles = tend - tbeg, tfirst = TYPE == 1 ? tend - 1 : tbeg;
;     LAS float* xm = (LAS float*)(lds + LDS_BYTES - 2048);
;     ADMA(tfirst, tfirst & 1);
;     asm volatile("s_waitcnt vmcnt(0)" ::: "memory");
;     __syncthreads();
;     int kb[4], kbr[4];
; #pragma unroll
;     for (int dd = 0; dd < 4; ++dd) { kb[dd] = r32 * 256 + ((((dd * 2 + hi) ^ (r32 & 7))) << 4); kbr[dd] = 16384 + r32 * 128 + ((((dd * 2 + hi) ^ (r32 & 7))) << 4); }
	s_cbranch_scc1 .LBB0_830
	v_lshlrev_b32_e32 v13, 4, v227
	v_lshlrev_b32_e32 v12, 3, v227
	v_and_b32_e32 v13, 0xc0, v13
	v_lshlrev_b32_e32 v14, 1, v227
	v_and_b32_e32 v11, 15, v2
	v_and_or_b32 v13, v12, 24, v13
	v_and_b32_e32 v14, 32, v14
	v_and_b32_e32 v12, 0x100, v12
	v_or3_b32 v12, v13, v14, v12
	v_xor_b32_e32 v13, v225, v11
	s_or_b32 s10, s2, 63
	v_lshlrev_b32_e32 v230, 4, v13
	v_bitop3_b32 v13, v225, v11, 2 bitop3:0x36
	v_lshlrev_b32_e32 v231, 4, v13
	v_bitop3_b32 v13, v225, v11, 4 bitop3:0x36
	s_add_u32 s28, s40, 0x27d62000
	v_lshlrev_b32_e32 v232, 4, v13
	v_add_u32_e32 v234, 0, v12
	s_addc_u32 s29, s41, 0
	v_add3_u32 v12, s6, v7, v8
	v_mov_b32_e32 v13, v1
	s_or_b32 s19, s38, s19
	v_lshl_add_u64 v[200:201], s[28:29], 0, v[12:13]
	s_add_u32 s28, s19, 0x25ca0100
	s_addc_u32 s29, s39, 0
	s_add_i32 s31, s31, s30
	s_lshl_b32 s30, s13, 6
	s_addk_i32 s30, 0x200
	v_or_b32_e32 v8, s30, v227
	v_add_u32_e32 v7, s31, v6
	v_lshlrev_b32_e32 v8, 1, v8
	v_and_b32_e32 v2, 3, v2
	v_add_lshl_u32 v7, v7, v3, 12
	v_and_b32_e32 v8, 0xc0, v8
	v_lshlrev_b32_e32 v2, 4, v2
	s_add_i32 s18, s18, s12
	v_or3_b32 v12, v7, v8, v2
	v_add3_u32 v2, s18, v6, v3
	v_add_u32_e32 v3, s11, v4
	s_add_u32 s18, s19, 0x25ca0000
	v_add_lshl_u32 v3, v3, v5, 1
	s_addc_u32 s19, s39, 0
	s_lshl_b32 s11, s13, 14
	v_lshl_or_b32 v2, v2, 12, v3
	v_mov_b32_e32 v3, v1
	s_add_i32 s12, s11, 0x20000
	v_lshlrev_b32_e32 v4, 12, v223
	v_lshl_add_u64 v[204:205], s[28:29], 0, v[2:3]
	v_or3_b32 v2, s12, v4, v10
	v_bitop3_b32 v11, v225, v11, 6 bitop3:0x36
	v_lshl_add_u64 v[206:207], s[18:19], 0, v[2:3]
	v_or3_b32 v2, s11, v4, v9
	v_mov_b32_e32 v16, v1
	v_mov_b32_e32 v17, v1
	v_lshlrev_b32_e32 v233, 4, v11
	v_lshl_add_u64 v[202:203], s[28:29], 0, v[12:13]
	v_lshl_add_u64 v[208:209], s[18:19], 0, v[2:3]
	v_mov_b32_e32 v2, v1
	v_mov_b32_e32 v4, v1
	v_mov_b32_e32 v5, v1
	v_mov_b32_e32 v6, v1
	v_mov_b32_e32 v7, v1
	v_mov_b32_e32 v8, v1
	v_mov_b32_e32 v9, v1
	v_mov_b32_e32 v10, v1
	v_mov_b32_e32 v11, v1
	v_mov_b32_e32 v12, v1
	v_mov_b32_e32 v14, v1
	v_mov_b32_e32 v15, v1
	v_mov_b64_e32 v[64:65], v[16:17]
	v_mov_b64_e32 v[48:49], v[16:17]
	v_mov_b64_e32 v[32:33], v[16:17]
	v_lshlrev_b32_e32 v228, 8, v226
	v_lshlrev_b32_e32 v229, 7, v226
	v_lshl_add_u32 v235, v226, 2, s3
	s_lshl_b32 s11, s14, 6
	s_mov_b32 s12, 0
	v_mov_b32_e32 v199, 0
	v_mov_b32_e32 v198, 0xf149f2ca
	v_add_u32_e32 v0, s3, v0
	v_mov_b64_e32 v[62:63], v[14:15]
	v_mov_b64_e32 v[60:61], v[12:13]
	v_mov_b64_e32 v[58:59], v[10:11]
	v_mov_b64_e32 v[56:57], v[8:9]
	v_mov_b64_e32 v[54:55], v[6:7]
	v_mov_b64_e32 v[52:53], v[4:5]
	v_mov_b64_e32 v[50:51], v[2:3]
	v_mov_b64_e32 v[46:47], v[14:15]
	v_mov_b64_e32 v[44:45], v[12:13]
	v_mov_b64_e32 v[42:43], v[10:11]
	v_mov_b64_e32 v[40:41], v[8:9]
	v_mov_b64_e32 v[38:39], v[6:7]
	v_mov_b64_e32 v[36:37], v[4:5]
	v_mov_b64_e32 v[34:35], v[2:3]
	v_mov_b64_e32 v[30:31], v[14:15]
	v_mov_b64_e32 v[28:29], v[12:13]
	v_mov_b64_e32 v[26:27], v[10:11]
	v_mov_b64_e32 v[24:25], v[8:9]
	v_mov_b64_e32 v[22:23], v[6:7]
	v_mov_b64_e32 v[20:21], v[4:5]
	v_mov_b64_e32 v[18:19], v[2:3]
	v_readlane_b32 s31, v254, 57
	v_readlane_b32 s30, v254, 23
	s_branch .LBB0_819

; #define LAS __attribute__((address_space(3)))
; #define SBAR() __builtin_amdgcn_sched_barrier(0)
; template <int TYPE>
; __device__ __forceinline__ void attn_item(const Params& p, int layer, int head, int qb, int mode, LAS unsigned char* lds) {
;     ...
;     for (int it2 = 0; it2 < ntiles; ++it2) {
;         const int t = TYPE == 1 ? tfirst - it2 : tfirst + it2, tn = TYPE == 1 ? t - 1 : t + 1;
;         const int bf = t & 1, kbase = t * 64;
;         if (it2 + 1 < ntiles) { ADMA(tn, bf ^ 1); }
;         if (kbase <= w_last) {
;             f32x16 p0 = (f32x16){}, p1 = (f32x16){};
;             const LAS unsigned char* kt = K_lds + bf * SHM_K;
; #pragma unroll
;             for (int d0 = 0; d0 < NQ; ++d0) {
;                 const LAS unsigned char* a = d0 < 8 ? kt + kb[d0 & 3] + (d0 >> 2) * 128 : kt + kbr[d0 & 3];
;                 const bf16x8 b0 = *(const LAS bf16x8*)a, b1 = *(const LAS bf16x8*)(a + (d0 < 8 ? 32 * 256 : 32 * 128));
;                 p0 = __builtin_amdgcn_mfma_f32_32x32x16_bf16(b0, qr[d0], p0, 0, 0, 0);
;                 p1 = __builtin_amdgcn_mfma_f32_32x32x16_bf16(b1, qr[d0], p1, 0, 0, 0);
;                 if ((d0 & 3) == 3) SBAR();
;             }
;             if (TYPE == 1) {
;                 const LAS float* bb = B_lds + bf * 64 + 4 * hi;
; #pragma unroll
;                 for (int q4 = 0; q4 < 4; ++q4) {
;                     const f32x4 b0 = *(const LAS f32x4*)(bb + 8 * q4), b1 = *(const LAS f32x4*)(bb + 32 + 8 * q4);
; #pragma unroll
;                     for (int j = 0; j < 4; ++j) { p0[q4 * 4 + j] += b0[j]; p1[q4 * 4 + j] += b1[j]; }
;                 }
;             }
;             if (TYPE == 1 && kbase + 63 > w_first) {
;                 const int lim = my_kmax - kbase - 4 * hi; const float NEGI = -__builtin_inff();
; #pragma unroll
;                 for (int r = 0; r < 16; ++r) { const int c = (r & 3) + 8 * (r >> 2); if (c > lim) p0[r] = NEGI; if (c + 32 > lim) p1[r] = NEGI; }
;             }
;             if (t == T0) {
;                 const int lo = (PADR & 63) - 4 * hi; const float NEGI = -__builtin_inff();
; #pragma unroll
;                 for (int r = 0; r < 16; ++r) { const int c = (r & 3) + 8 * (r >> 2); if (c < lo) p0[r] = NEGI; if (c + 32 < lo) p1[r] = NEGI; }
;             }
.LBB0_821:
	s_cmp_gt_i32 s11, s10
	s_cbranch_scc1 .LBB0_818
	s_mul_i32 s19, s28, 0x6000
	s_add_i32 s19, s19, 0
	v_add_u32_e32 v102, s19, v230
	v_add_u32_e32 v103, v102, v228
	v_add_u32_e32 v104, s19, v231
	v_add_u32_e32 v105, v104, v228
	v_add_u32_e32 v106, s19, v232
	v_add_u32_e32 v107, v106, v228
	v_add_u32_e32 v108, s19, v233
	v_add_u32_e32 v109, v108, v228
	v_xor_b32_e32 v194, 0x80, v103
	v_xor_b32_e32 v195, 0x80, v105
	v_xor_b32_e32 v196, 0x80, v107
	v_xor_b32_e32 v197, 0x80, v109
	v_and_b32_e32 v248, 0xffffff7f, v102
	v_and_b32_e32 v249, 0xffffff7f, v104
	v_and_b32_e32 v250, 0xffffff7f, v106
	v_and_b32_e32 v251, 0xffffff7f, v108
	v_add_u32_e32 v248, v248, v229
	v_add_u32_e32 v249, v249, v229
	v_add_u32_e32 v250, v250, v229
	v_add_u32_e32 v251, v251, v229
	ds_read_b128 v[98:101], v103 offset:32768
	ds_read_b128 v[110:113], v103 offset:40960
	ds_read_b128 v[114:117], v105 offset:32768
	ds_read_b128 v[118:121], v105 offset:40960
	ds_read_b128 v[122:125], v107 offset:32768
	ds_read_b128 v[126:129], v107 offset:40960
	ds_read_b128 v[178:181], v109 offset:32768
	ds_read_b128 v[182:185], v109 offset:40960
	ds_read_b128 v[186:189], v194 offset:32768
	ds_read_b128 v[190:193], v194 offset:40960
	ds_read_b128 v[240:243], v195 offset:32768
	ds_read_b128 v[244:247], v195 offset:40960
	s_waitcnt lgkmcnt(11)
	v_mfma_f32_32x32x16_bf16 v[82:97], v[98:101], v[130:133], 0
	ds_read_b128 v[98:101], v196 offset:32768
	s_waitcnt lgkmcnt(11)
	v_mfma_f32_32x32x16_bf16 v[66:81], v[110:113], v[130:133], 0
	ds_read_b128 v[110:113], v196 offset:40960
	s_waitcnt lgkmcnt(11)
	v_mfma_f32_32x32x16_bf16 v[82:97], v[114:117], v[134:137], v[82:97]
	ds_read_b128 v[114:117], v197 offset:32768
	s_waitcnt lgkmcnt(11)
	v_mfma_f32_32x32x16_bf16 v[66:81], v[118:121], v[134:137], v[66:81]
	ds_read_b128 v[118:121], v197 offset:40960
	s_waitcnt lgkmcnt(11)
	v_mfma_f32_32x32x16_bf16 v[82:97], v[122:125], v[138:141], v[82:97]
	ds_read_b128 v[122:125], v248 offset:49152
	s_waitcnt lgkmcnt(11)
	v_mfma_f32_32x32x16_bf16 v[66:81], v[126:129], v[138:141], v[66:81]
	ds_read_b128 v[126:129], v248 offset:53248
	s_waitcnt lgkmcnt(11)
	v_mfma_f32_32x32x16_bf16 v[82:97], v[178:181], v[142:145], v[82:97]
	ds_read_b128 v[178:181], v249 offset:49152
	s_waitcnt lgkmcnt(11)
	v_mfma_f32_32x32x16_bf16 v[66:81], v[182:185], v[142:145], v[66:81]
	ds_read_b128 v[182:185], v249 offset:53248
	s_waitcnt lgkmcnt(11)
	v_mfma_f32_32x32x16_bf16 v[82:97], v[186:189], v[146:149], v[82:97]
	ds_read_b128 v[186:189], v250 offset:49152
	s_waitcnt lgkmcnt(11)
	v_mfma_f32_32x32x16_bf16 v[66:81], v[190:193], v[146:149], v[66:81]
	ds_read_b128 v[190:193], v250 offset:53248
	s_waitcnt lgkmcnt(11)
	v_mfma_f32_32x32x16_bf16 v[82:97], v[240:243], v[150:153], v[82:97]
	ds_read_b128 v[240:243], v251 offset:49152
	s_waitcnt lgkmcnt(11)
	v_mfma_f32_32x32x16_bf16 v[66:81], v[244:247], v[150:153], v[66:81]
	ds_read_b128 v[244:247], v251 offset:53248
	s_waitcnt lgkmcnt(11)
	v_mfma_f32_32x32x16_bf16 v[82:97], v[98:101], v[154:157], v[82:97]
	s_waitcnt lgkmcnt(10)
	v_mfma_f32_32x32x16_bf16 v[66:81], v[110:113], v[154:157], v[66:81]
	s_waitcnt lgkmcnt(9)
	v_mfma_f32_32x32x16_bf16 v[82:97], v[114:117], v[158:161], v[82:97]
	s_waitcnt lgkmcnt(8)
	v_mfma_f32_32x32x16_bf16 v[66:81], v[118:121], v[158:161], v[66:81]
	s_waitcnt lgkmcnt(7)
	v_mfma_f32_32x32x16_bf16 v[82:97], v[122:125], v[162:165], v[82:97]
	s_waitcnt lgkmcnt(6)
	v_mfma_f32_32x32x16_bf16 v[66:81], v[126:129], v[162:165], v[66:81]
	s_waitcnt lgkmcnt(5)
	v_mfma_f32_32x32x16_bf16 v[82:97], v[178:181], v[166:169], v[82:97]
	s_waitcnt lgkmcnt(4)
	v_mfma_f32_32x32x16_bf16 v[66:81], v[182:185], v[166:169], v[66:81]
	s_waitcnt lgkmcnt(3)
	v_mfma_f32_32x32x16_bf16 v[82:97], v[186:189], v[170:173], v[82:97]
	s_waitcnt lgkmcnt(2)
	v_mfma_f32_32x32x16_bf16 v[66:81], v[190:193], v[170:173], v[66:81]
	s_waitcnt lgkmcnt(1)
	v_mfma_f32_32x32x16_bf16 v[82:97], v[240:243], v[174:177], v[82:97]
	s_waitcnt lgkmcnt(0)
	v_mfma_f32_32x32x16_bf16 v[66:81], v[244:247], v[174:177], v[66:81]
	s_cmp_eq_u32 s18, 3
	s_cselect_b64 vcc, -1, 0
	s_nop 7
	s_cbranch_scc0 .Lmla_nomask
	v_cndmask_b32_e32 v82, v82, v219, vcc
	v_cndmask_b32_e32 v83, v83, v219, vcc
	v_cndmask_b32_e32 v85, v85, v219, vcc
	v_cndmask_b32_e32 v84, v84, v219, vcc
	v_cndmask_b32_e32 v87, v87, v219, vcc
	v_cndmask_b32_e32 v86, v86, v219, vcc
	v_cndmask_b32_e32 v89, v89, v219, vcc
	v_cndmask_b32_e32 v88, v88, v219, vcc
	v_cndmask_b32_e32 v91, v91, v219, vcc
	v_cndmask_b32_e32 v90, v90, v219, vcc
	v_cndmask_b32_e32 v93, v93, v219, vcc
	v_cndmask_b32_e32 v92, v92, v219, vcc
	v_cndmask_b32_e32 v95, v95, v219, vcc
	v_cndmask_b32_e32 v94, v94, v219, vcc
	v_cndmask_b32_e32 v97, v97, v219, vcc
	v_cndmask_b32_e32 v96, v96, v219, vcc
	v_cndmask_b32_e32 v67, v67, v219, vcc
	v_cndmask_b32_e32 v66, v66, v219, vcc
	v_cndmask_b32_e32 v69, v69, v219, vcc
	v_cndmask_b32_e32 v68, v68, v219, vcc
	v_cndmask_b32_e32 v71, v71, v219, vcc
	v_cndmask_b32_e32 v70, v70, v219, vcc
	v_cndmask_b32_e32 v73, v73, v219, vcc
	v_cndmask_b32_e32 v72, v72, v219, vcc
